# q4 phase: 32 non-scan blocks (two per chain group, same XCD) first touch the group's per-chunk W/Q/KT/attn/U tile lines into L2 ahead of the eight recurrence blocks, then join the queue
# baseline (speedup 1.0000x reference)
.Lscan_helper:
	v_readlane_b32 s98, v255, 18
	s_cmpk_gt_i32 s98, 0x9f
	s_cbranch_scc1 .LBB0_569
	s_and_b32 s99, s98, 7
	s_sub_i32 s98, s98, 0x80
	s_lshr_b32 s98, s98, 3
	s_and_b32 s100, s98, 1
	s_lshl_b32 s99, s99, 1
	s_or_b32 s99, s99, s100
	s_lshr_b32 s98, s98, 1
	s_lshr_b32 s100, s99, 2
	s_and_b32 s99, s99, 3
	s_lshl_b32 s100, s100, 22
	s_lshl_b32 s101, s99, 8
	s_add_i32 s100, s100, s101
	v_readfirstlane_b32 s101, v228
	s_lshr_b32 s101, s101, 6
	s_cmp_eq_u32 s98, 0
	s_cbranch_scc0 .Lsh_half1
	s_cmp_gt_u32 s101, 3
	s_cbranch_scc1 .LBB0_569
	v_bfe_u32 v176, v228, 1, 6
	v_and_b32_e32 v177, 1, v228
	v_lshlrev_b32_e32 v176, 10, v176
	v_lshl_or_b32 v176, v177, 7, v176
	v_add_u32_e32 v176, s100, v176
	v_mov_b32_e32 v178, 0x1e505000
	v_mov_b32_e32 v177, 0x170c0000
	v_cmp_gt_u32_e32 vcc, 0x80, v228
	v_cndmask_b32_e32 v177, v177, v178, vcc
	v_add_co_u32_e32 v178, vcc, v177, v176
	v_addc_co_u32_e64 v179, vcc, 0, 0, vcc
	v_mov_b32_e32 v180, 0x10000
	s_branch .Lsh_go
.Lsh_half1:
	s_cmp_gt_u32 s101, 4
	s_cbranch_scc1 .LBB0_569
	v_bfe_u32 v176, v228, 1, 6
	v_and_b32_e32 v177, 1, v228
	v_lshlrev_b32_e32 v176, 10, v176
	v_lshl_or_b32 v176, v177, 7, v176
	v_add_u32_e32 v176, s100, v176
	v_mov_b32_e32 v177, 0x180c0000
	v_mov_b32_e32 v180, 0x10000
	v_lshrrev_b32_e32 v179, 1, v228
	v_add_u32_e32 v179, 32, v179
	v_and_b32_e32 v179, 63, v179
	v_lshlrev_b32_e32 v179, 10, v179
	v_and_b32_e32 v181, 1, v228
	v_lshl_or_b32 v179, v181, 7, v179
	v_add_u32_e32 v179, s100, v179
	v_cmp_lt_u32_e32 vcc, 0xbf, v228
	v_cndmask_b32_e32 v176, v176, v179, vcc
	v_mov_b32_e32 v179, 0x1d505000
	v_cndmask_b32_e32 v177, v177, v179, vcc
	s_lshr_b32 s100, s100, 1
	v_subrev_u32_e32 v179, 0x80, v228
	v_lshlrev_b32_e32 v179, 9, v179
	v_add_u32_e32 v179, s100, v179
	v_cmp_lt_u32_e32 vcc, 0x7f, v228
	v_mov_b32_e32 v181, 0xc0
	v_cmp_gt_u32_e64 s[100:101], v181, v228
	s_and_b64 vcc, vcc, s[100:101]
	v_cndmask_b32_e32 v176, v176, v179, vcc
	v_mov_b32_e32 v179, 0x1f505000
	v_cndmask_b32_e32 v177, v177, v179, vcc
	v_mov_b32_e32 v179, 0x8000
	v_cndmask_b32_e32 v180, v180, v179, vcc
	v_add_co_u32_e32 v178, vcc, v177, v176
	v_addc_co_u32_e64 v179, vcc, 0, 0, vcc
.Lsh_go:
	v_mov_b32_e32 v181, 0
	v_lshl_add_u64 v[178:179], s[44:45], 0, v[178:179]
	s_movk_i32 s98, 0x40
.Lsh_loop:
	global_load_dword v176, v[178:179], off
	v_lshl_add_u64 v[178:179], v[178:179], 0, v[180:181]
	s_add_i32 s98, s98, -1
	s_waitcnt vmcnt(2)
	s_cmp_lg_u32 s98, 0
	s_cbranch_scc1 .Lsh_loop
	s_branch .LBB0_569
